# HGRN gate prologue with packed f32 ops (v_pk_mul/add/fma_f32 on value pairs, constants broadcast via op_sel) on top of the log2-domain version
# speedup vs baseline: 1.0027x; 1.0022x over previous
.LBB0_234:
	s_mov_b32 s100, 0x3fb8aa3b
	s_mov_b32 s101, 1.0
	v_mov_b32_e32 v221, 0x42ad1f97
	v_sub_f32_e32 v220, 1.0, v36
	v_lshlrev_b32_e32 v186, 16, v40
	v_lshlrev_b32_e32 v187, 16, v51
	v_lshlrev_b32_e32 v196, 16, v50
	v_lshlrev_b32_e32 v197, 16, v49
	v_pk_mul_f32 v[186:187], v[186:187], s[100:101] op_sel_hi:[1,0]
	v_pk_mul_f32 v[196:197], v[196:197], s[100:101] op_sel_hi:[1,0]
	v_min_f32_e64 v188, -v186, v221
	v_min_f32_e64 v189, -v187, v221
	v_min_f32_e64 v198, -v196, v221
	v_min_f32_e64 v199, -v197, v221
	v_exp_f32_e32 v188, v188
	v_exp_f32_e32 v189, v189
	v_exp_f32_e32 v198, v198
	v_exp_f32_e32 v199, v199
	v_pk_add_f32 v[190:191], v[188:189], s[100:101] op_sel:[0,1] op_sel_hi:[1,1]
	v_pk_add_f32 v[200:201], v[198:199], s[100:101] op_sel:[0,1] op_sel_hi:[1,1]
	v_pk_fma_f32 v[194:195], v[188:189], v[36:37], s[100:101] op_sel:[0,0,1] op_sel_hi:[1,0,1]
	v_pk_fma_f32 v[204:205], v[198:199], v[36:37], s[100:101] op_sel:[0,0,1] op_sel_hi:[1,0,1]
	v_rcp_f32_e32 v192, v190
	v_rcp_f32_e32 v193, v191
	v_rcp_f32_e32 v202, v200
	v_rcp_f32_e32 v203, v201
	v_log_f32_e32 v190, v190
	v_log_f32_e32 v191, v191
	v_log_f32_e32 v200, v200
	v_log_f32_e32 v201, v201
	v_log_f32_e32 v194, v194
	v_log_f32_e32 v195, v195
	v_log_f32_e32 v204, v204
	v_log_f32_e32 v205, v205
	v_pk_mul_f32 v[192:193], v[188:189], v[192:193]
	v_pk_mul_f32 v[202:203], v[198:199], v[202:203]
	v_min_f32_e64 v190, v186, -v190
	v_min_f32_e64 v191, v187, -v191
	v_min_f32_e64 v200, v196, -v200
	v_min_f32_e64 v201, v197, -v201
	v_pk_mul_f32 v[144:145], v[192:193], v[220:221] op_sel_hi:[1,0]
	v_pk_mul_f32 v[146:147], v[202:203], v[220:221] op_sel_hi:[1,0]
	v_pk_add_f32 v[190:191], v[190:191], v[194:195]
	v_pk_add_f32 v[200:201], v[200:201], v[204:205]
	v_add_f32_e32 v128, 0, v190
	v_add_f32_e32 v129, v191, v128
	v_add_f32_e32 v130, v200, v129
	v_add_f32_e32 v131, v201, v130
	v_lshlrev_b32_e32 v186, 16, v48
	v_lshlrev_b32_e32 v187, 16, v47
	v_lshlrev_b32_e32 v196, 16, v46
	v_lshlrev_b32_e32 v197, 16, v45
	v_pk_mul_f32 v[186:187], v[186:187], s[100:101] op_sel_hi:[1,0]
	v_pk_mul_f32 v[196:197], v[196:197], s[100:101] op_sel_hi:[1,0]
	v_min_f32_e64 v188, -v186, v221
	v_min_f32_e64 v189, -v187, v221
	v_min_f32_e64 v198, -v196, v221
	v_min_f32_e64 v199, -v197, v221
	v_exp_f32_e32 v188, v188
	v_exp_f32_e32 v189, v189
	v_exp_f32_e32 v198, v198
	v_exp_f32_e32 v199, v199
	v_pk_add_f32 v[190:191], v[188:189], s[100:101] op_sel:[0,1] op_sel_hi:[1,1]
	v_pk_add_f32 v[200:201], v[198:199], s[100:101] op_sel:[0,1] op_sel_hi:[1,1]
	v_pk_fma_f32 v[194:195], v[188:189], v[36:37], s[100:101] op_sel:[0,0,1] op_sel_hi:[1,0,1]
	v_pk_fma_f32 v[204:205], v[198:199], v[36:37], s[100:101] op_sel:[0,0,1] op_sel_hi:[1,0,1]
	v_rcp_f32_e32 v192, v190
	v_rcp_f32_e32 v193, v191
	v_rcp_f32_e32 v202, v200
	v_rcp_f32_e32 v203, v201
	v_log_f32_e32 v190, v190
	v_log_f32_e32 v191, v191
	v_log_f32_e32 v200, v200
	v_log_f32_e32 v201, v201
	v_log_f32_e32 v194, v194
	v_log_f32_e32 v195, v195
	v_log_f32_e32 v204, v204
	v_log_f32_e32 v205, v205
	v_pk_mul_f32 v[192:193], v[188:189], v[192:193]
	v_pk_mul_f32 v[202:203], v[198:199], v[202:203]
	v_min_f32_e64 v190, v186, -v190
	v_min_f32_e64 v191, v187, -v191
	v_min_f32_e64 v200, v196, -v200
	v_min_f32_e64 v201, v197, -v201
	v_pk_mul_f32 v[148:149], v[192:193], v[220:221] op_sel_hi:[1,0]
	v_pk_mul_f32 v[150:151], v[202:203], v[220:221] op_sel_hi:[1,0]
	v_pk_add_f32 v[190:191], v[190:191], v[194:195]
	v_pk_add_f32 v[200:201], v[200:201], v[204:205]
	v_add_f32_e32 v132, v190, v131
	v_add_f32_e32 v133, v191, v132
	v_add_f32_e32 v134, v200, v133
	v_add_f32_e32 v135, v201, v134
	v_lshlrev_b32_e32 v186, 16, v44
	v_lshlrev_b32_e32 v187, 16, v43
	v_lshlrev_b32_e32 v196, 16, v42
	v_lshlrev_b32_e32 v197, 16, v41
	v_pk_mul_f32 v[186:187], v[186:187], s[100:101] op_sel_hi:[1,0]
	v_pk_mul_f32 v[196:197], v[196:197], s[100:101] op_sel_hi:[1,0]
	v_min_f32_e64 v188, -v186, v221
	v_min_f32_e64 v189, -v187, v221
	v_min_f32_e64 v198, -v196, v221
	v_min_f32_e64 v199, -v197, v221
	v_exp_f32_e32 v188, v188
	v_exp_f32_e32 v189, v189
	v_exp_f32_e32 v198, v198
	v_exp_f32_e32 v199, v199
	v_pk_add_f32 v[190:191], v[188:189], s[100:101] op_sel:[0,1] op_sel_hi:[1,1]
	v_pk_add_f32 v[200:201], v[198:199], s[100:101] op_sel:[0,1] op_sel_hi:[1,1]
	v_pk_fma_f32 v[194:195], v[188:189], v[36:37], s[100:101] op_sel:[0,0,1] op_sel_hi:[1,0,1]
	v_pk_fma_f32 v[204:205], v[198:199], v[36:37], s[100:101] op_sel:[0,0,1] op_sel_hi:[1,0,1]
	v_rcp_f32_e32 v192, v190
	v_rcp_f32_e32 v193, v191
	v_rcp_f32_e32 v202, v200
	v_rcp_f32_e32 v203, v201
	v_log_f32_e32 v190, v190
	v_log_f32_e32 v191, v191
	v_log_f32_e32 v200, v200
	v_log_f32_e32 v201, v201
	v_log_f32_e32 v194, v194
	v_log_f32_e32 v195, v195
	v_log_f32_e32 v204, v204
	v_log_f32_e32 v205, v205
	v_pk_mul_f32 v[192:193], v[188:189], v[192:193]
	v_pk_mul_f32 v[202:203], v[198:199], v[202:203]
	v_min_f32_e64 v190, v186, -v190
	v_min_f32_e64 v191, v187, -v191
	v_min_f32_e64 v200, v196, -v200
	v_min_f32_e64 v201, v197, -v201
	v_pk_mul_f32 v[152:153], v[192:193], v[220:221] op_sel_hi:[1,0]
	v_pk_mul_f32 v[154:155], v[202:203], v[220:221] op_sel_hi:[1,0]
	v_pk_add_f32 v[190:191], v[190:191], v[194:195]
	v_pk_add_f32 v[200:201], v[200:201], v[204:205]
	v_add_f32_e32 v136, v190, v135
	v_add_f32_e32 v137, v191, v136
	v_add_f32_e32 v138, v200, v137
	v_add_f32_e32 v139, v201, v138
	v_lshlrev_b32_e32 v186, 16, v39
	v_lshlrev_b32_e32 v187, 16, v38
	v_lshlrev_b32_e32 v196, 16, v37
	v_lshlrev_b32_e32 v197, 16, v35
	v_pk_mul_f32 v[186:187], v[186:187], s[100:101] op_sel_hi:[1,0]
	v_pk_mul_f32 v[196:197], v[196:197], s[100:101] op_sel_hi:[1,0]
	v_min_f32_e64 v188, -v186, v221
	v_min_f32_e64 v189, -v187, v221
	v_min_f32_e64 v198, -v196, v221
	v_min_f32_e64 v199, -v197, v221
	v_exp_f32_e32 v188, v188
	v_exp_f32_e32 v189, v189
	v_exp_f32_e32 v198, v198
	v_exp_f32_e32 v199, v199
	v_pk_add_f32 v[190:191], v[188:189], s[100:101] op_sel:[0,1] op_sel_hi:[1,1]
	v_pk_add_f32 v[200:201], v[198:199], s[100:101] op_sel:[0,1] op_sel_hi:[1,1]
	v_pk_fma_f32 v[194:195], v[188:189], v[36:37], s[100:101] op_sel:[0,0,1] op_sel_hi:[1,0,1]
	v_pk_fma_f32 v[204:205], v[198:199], v[36:37], s[100:101] op_sel:[0,0,1] op_sel_hi:[1,0,1]
	v_rcp_f32_e32 v192, v190
	v_rcp_f32_e32 v193, v191
	v_rcp_f32_e32 v202, v200
	v_rcp_f32_e32 v203, v201
	v_log_f32_e32 v190, v190
	v_log_f32_e32 v191, v191
	v_log_f32_e32 v200, v200
	v_log_f32_e32 v201, v201
	v_log_f32_e32 v194, v194
	v_log_f32_e32 v195, v195
	v_log_f32_e32 v204, v204
	v_log_f32_e32 v205, v205
	v_pk_mul_f32 v[192:193], v[188:189], v[192:193]
	v_pk_mul_f32 v[202:203], v[198:199], v[202:203]
	v_min_f32_e64 v190, v186, -v190
	v_min_f32_e64 v191, v187, -v191
	v_min_f32_e64 v200, v196, -v200
	v_min_f32_e64 v201, v197, -v201
	v_pk_mul_f32 v[156:157], v[192:193], v[220:221] op_sel_hi:[1,0]
	v_pk_mul_f32 v[158:159], v[202:203], v[220:221] op_sel_hi:[1,0]
	v_pk_add_f32 v[190:191], v[190:191], v[194:195]
	v_pk_add_f32 v[200:201], v[200:201], v[204:205]
	v_add_f32_e32 v140, v190, v139
	v_add_f32_e32 v141, v191, v140
	v_add_f32_e32 v142, v200, v141
	v_add_f32_e32 v143, v201, v142
	s_mov_b32 s3, 0xbfb8aa3b
	v_lshrrev_b32_e32 v28, 8, v28
	s_movk_i32 s2, 0x410
	v_mul_i32_i24_e32 v28, 0xd800, v28
	v_mad_u32_u24 v40, v29, s2, v21
	v_lshl_add_u32 v40, v40, 2, v28
	v_mov_b32_e32 v160, v40
	v_add_u32_e32 v52, 0x4400, v40
	v_and_b32_e32 v33, 0xff, v33
	v_mul_u32_u24_e32 v31, 0x48, v31
	v_add_u32_e32 v51, 0x400, v40
	v_add_u32_e32 v49, 0x4800, v40
	v_lshlrev_b32_e32 v31, 1, v31
	v_lshlrev_b32_e32 v30, 1, v30
	v_cmp_lt_u32_e32 vcc, 63, v33
	s_nop 0
	v_add_u32_e32 v47, 0x800, v40
	v_add_u32_e32 v45, 0x4c00, v40
	s_nop 0
	s_nop 0
	v_add_u32_e32 v43, 0xc00, v40
	v_add_u32_e32 v40, 0x5000, v40
	v_lshl_add_u32 v34, v33, 2, v28
	v_add_u32_e32 v161, 0x400, v160
	v_add_u32_e32 v162, 0x800, v160
	v_add_u32_e32 v163, 0xc00, v160
	v_add_u32_e32 v164, 0x4400, v160
	v_add_u32_e32 v165, 0x4800, v160
	v_add_u32_e32 v166, 0x4c00, v160
	v_add_u32_e32 v167, 0x5000, v160
	ds_write2_b32 v160, v128, v129 offset1:65
	ds_write2_b32 v164, v144, v145 offset1:65
	ds_write2_b32 v160, v130, v131 offset0:130 offset1:195
	ds_write2_b32 v164, v146, v147 offset0:130 offset1:195
	ds_write2_b32 v161, v132, v133 offset0:4 offset1:69
	ds_write2_b32 v165, v148, v149 offset0:4 offset1:69
	ds_write2_b32 v161, v134, v135 offset0:134 offset1:199
	ds_write2_b32 v165, v150, v151 offset0:134 offset1:199
	ds_write2_b32 v162, v136, v137 offset0:8 offset1:73
	ds_write2_b32 v166, v152, v153 offset0:8 offset1:73
	ds_write2_b32 v162, v138, v139 offset0:138 offset1:203
	ds_write2_b32 v166, v154, v155 offset0:138 offset1:203
	ds_write2_b32 v167, v156, v157 offset0:12 offset1:77
	ds_write2_b32 v163, v140, v141 offset0:12 offset1:77
	ds_write2_b32 v163, v142, v143 offset0:142 offset1:207
	ds_write2_b32 v167, v158, v159 offset0:142 offset1:207
	ds_write_b32 v34, v143 offset:53248
	v_add3_u32 v34, v28, v31, v30
	v_add3_u32 v30, v28, v30, v31
	ds_write_b16 v34, v12 offset:34816
	ds_write_b16_d16_hi v30, v12 offset:34960
	ds_write_b16 v34, v13 offset:35104
	ds_write_b16_d16_hi v30, v13 offset:35248
	ds_write_b16 v34, v14 offset:35392
	ds_write_b16_d16_hi v30, v14 offset:35536
	ds_write_b16 v34, v15 offset:35680
	ds_write_b16_d16_hi v30, v15 offset:35824
	ds_write_b16 v34, v8 offset:35968
	ds_write_b16_d16_hi v30, v8 offset:36112
	ds_write_b16 v34, v9 offset:36256
	ds_write_b16_d16_hi v30, v9 offset:36400
	ds_write_b16 v34, v10 offset:36544
	ds_write_b16_d16_hi v30, v10 offset:36688
	ds_write_b16 v34, v11 offset:36832
	ds_write_b16_d16_hi v30, v11 offset:36976
	s_waitcnt lgkmcnt(0)
	s_barrier
	s_and_saveexec_b64 s[2:3], vcc
	s_cbranch_execz .LBB0_238
	v_lshlrev_b32_e32 v8, 2, v21
	s_mov_b32 s4, 0xd000
	v_add3_u32 v8, v28, v8, s4
	v_mov_b32_e32 v20, 0
	s_mov_b64 s[4:5], 0
